# phase 2c item epilogue: the seven later (gate piece, gain vector) load pairs issued up front instead of one dependent round trip per group
# baseline (speedup 1.0000x reference)
.LBB0_968:
	v_mul_f32_e32 v34, v79, v106
	v_mul_f32_e32 v34, 0xbfb8aa3b, v34
	v_exp_f32_e32 v42, v34
	v_mul_f32_e32 v34, v96, v107
	v_mul_f32_e32 v34, 0xbfb8aa3b, v34
	v_exp_f32_e32 v44, v34
	v_lshlrev_b32_e32 v36, 16, v62
	v_and_b32_e32 v37, 0xffff0000, v62
	v_pk_mul_f32 v[34:35], v[42:43], v[36:37] op_sel_hi:[0,1]
	v_pk_mul_f32 v[36:37], v[44:45], v[36:37] op_sel_hi:[0,1]
	v_cvt_pk_bf16_f32 v38, v36, v37
	v_lshlrev_b32_e32 v36, 16, v63
	v_and_b32_e32 v37, 0xffff0000, v63
	v_pk_mul_f32 v[40:41], v[42:43], v[36:37] op_sel_hi:[0,1]
	v_cvt_pk_bf16_f32 v34, v34, v35
	v_cvt_pk_bf16_f32 v35, v40, v41
	v_pk_mul_f32 v[36:37], v[44:45], v[36:37] op_sel_hi:[0,1]
	v_lshlrev_b32_e32 v40, 16, v64
	v_and_b32_e32 v41, 0xffff0000, v64
	v_lshlrev_b32_e32 v46, 16, v65
	v_and_b32_e32 v47, 0xffff0000, v65
	v_cvt_pk_bf16_f32 v39, v36, v37
	v_pk_mul_f32 v[36:37], v[42:43], v[40:41] op_sel_hi:[0,1]
	v_pk_mul_f32 v[40:41], v[44:45], v[40:41] op_sel_hi:[0,1]
	v_pk_mul_f32 v[48:49], v[42:43], v[46:47] op_sel_hi:[0,1]
	v_pk_mul_f32 v[46:47], v[44:45], v[46:47] op_sel_hi:[0,1]
	v_cvt_pk_bf16_f32 v36, v36, v37
	v_cvt_pk_bf16_f32 v40, v40, v41
	v_cvt_pk_bf16_f32 v37, v48, v49
	v_cvt_pk_bf16_f32 v41, v46, v47
	ds_read_b128 v[46:49], v99 offset:45056
	ds_read_b128 v[62:65], v99 offset:35840
	ds_read_b128 v[106:109], v99 offset:35872
	s_waitcnt lgkmcnt(1)
	v_mfma_f32_32x32x16_bf16 v[18:33], v[62:65], v[34:37], v[18:33]
	s_lshl_b32 s0, s6, 1
	s_mov_b64 s[4:5], 0x1200
	s_add_i32 s37, s37, s84
	v_mfma_f32_32x32x16_bf16 v[18:33], v[46:49], v[38:41], v[18:33]
	ds_read_b128 v[46:49], v99 offset:40448
	ds_read_b128 v[62:65], v99 offset:49664
	s_waitcnt lgkmcnt(1)
	v_mfma_f32_32x32x16_bf16 v[2:17], v[46:49], v[34:37], v[2:17]
	v_lshlrev_b32_e32 v34, 16, v58
	v_and_b32_e32 v35, 0xffff0000, v58
	v_mul_f32_e64 v36, v42, v34
	v_mul_f32_e64 v37, v42, v35
	v_mul_f32_e64 v34, v44, v34
	v_mul_f32_e64 v35, v44, v35
	v_cvt_pk_bf16_f32 v34, v34, v35
	v_lshlrev_b32_e32 v46, 16, v61
	v_and_b32_e32 v47, 0xffff0000, v61
	s_waitcnt lgkmcnt(0)
	v_mfma_f32_32x32x16_bf16 v[2:17], v[62:65], v[38:41], v[2:17]
	v_cvt_pk_bf16_f32 v38, v36, v37
	v_lshlrev_b32_e32 v36, 16, v59
	v_and_b32_e32 v37, 0xffff0000, v59
	v_mul_f32_e64 v40, v42, v36
	v_mul_f32_e64 v41, v42, v37
	v_pk_mul_f32 v[36:37], v[44:45], v[36:37] op_sel_hi:[0,1]
	v_cvt_pk_bf16_f32 v35, v36, v37
	v_lshlrev_b32_e32 v36, 16, v60
	v_and_b32_e32 v37, 0xffff0000, v60
	v_cvt_pk_bf16_f32 v39, v40, v41
	v_pk_mul_f32 v[40:41], v[42:43], v[36:37] op_sel_hi:[0,1]
	v_pk_mul_f32 v[36:37], v[44:45], v[36:37] op_sel_hi:[0,1]
	v_pk_mul_f32 v[48:49], v[42:43], v[46:47] op_sel_hi:[0,1]
	v_pk_mul_f32 v[46:47], v[44:45], v[46:47] op_sel_hi:[0,1]
	v_cvt_pk_bf16_f32 v40, v40, v41
	v_cvt_pk_bf16_f32 v36, v36, v37
	v_cvt_pk_bf16_f32 v41, v48, v49
	v_cvt_pk_bf16_f32 v37, v46, v47
	ds_read_b128 v[46:49], v99 offset:45088
	v_mfma_f32_32x32x16_bf16 v[18:33], v[106:109], v[38:41], v[18:33]
	s_waitcnt lgkmcnt(0)
	v_mfma_f32_32x32x16_bf16 v[18:33], v[46:49], v[34:37], v[18:33]
	ds_read_b128 v[46:49], v99 offset:40480
	ds_read_b128 v[58:61], v99 offset:49696
	s_waitcnt lgkmcnt(1)
	v_mfma_f32_32x32x16_bf16 v[2:17], v[46:49], v[38:41], v[2:17]
	v_lshlrev_b32_e32 v46, 16, v57
	v_and_b32_e32 v47, 0xffff0000, v57
	v_mul_f32_e64 v48, v42, v46
	v_mul_f32_e64 v49, v42, v47
	v_mul_f32_e64 v46, v44, v46
	v_mul_f32_e64 v47, v44, v47
	s_waitcnt lgkmcnt(0)
	v_mfma_f32_32x32x16_bf16 v[2:17], v[58:61], v[34:37], v[2:17]
	v_lshlrev_b32_e32 v36, 16, v54
	v_and_b32_e32 v37, 0xffff0000, v54
	v_mul_f32_e64 v34, v42, v36
	v_mul_f32_e64 v35, v42, v37
	v_mul_f32_e64 v36, v44, v36
	v_mul_f32_e64 v37, v44, v37
	v_cvt_pk_bf16_f32 v38, v36, v37
	v_lshlrev_b32_e32 v36, 16, v55
	v_and_b32_e32 v37, 0xffff0000, v55
	v_pk_mul_f32 v[40:41], v[42:43], v[36:37] op_sel_hi:[0,1]
	v_cvt_pk_bf16_f32 v34, v34, v35
	v_cvt_pk_bf16_f32 v35, v40, v41
	v_pk_mul_f32 v[36:37], v[44:45], v[36:37] op_sel_hi:[0,1]
	v_lshlrev_b32_e32 v40, 16, v56
	v_and_b32_e32 v41, 0xffff0000, v56
	v_cvt_pk_bf16_f32 v39, v36, v37
	v_pk_mul_f32 v[36:37], v[42:43], v[40:41] op_sel_hi:[0,1]
	v_pk_mul_f32 v[40:41], v[44:45], v[40:41] op_sel_hi:[0,1]
	v_cvt_pk_bf16_f32 v36, v36, v37
	v_cvt_pk_bf16_f32 v40, v40, v41
	v_cvt_pk_bf16_f32 v37, v48, v49
	v_cvt_pk_bf16_f32 v41, v46, v47
	ds_read_b128 v[46:49], v99 offset:35904
	ds_read_b128 v[54:57], v99 offset:45120
	s_waitcnt lgkmcnt(1)
	v_mfma_f32_32x32x16_bf16 v[18:33], v[46:49], v[34:37], v[18:33]
	s_waitcnt lgkmcnt(0)
	v_mfma_f32_32x32x16_bf16 v[18:33], v[54:57], v[38:41], v[18:33]
	ds_read_b128 v[46:49], v99 offset:40512
	ds_read_b128 v[54:57], v99 offset:49728
	s_waitcnt lgkmcnt(1)
	v_mfma_f32_32x32x16_bf16 v[2:17], v[46:49], v[34:37], v[2:17]
	v_lshlrev_b32_e32 v36, 16, v50
	v_and_b32_e32 v37, 0xffff0000, v50
	v_mul_f32_e64 v34, v42, v36
	v_mul_f32_e64 v35, v42, v37
	v_mul_f32_e64 v36, v44, v36
	v_mul_f32_e64 v37, v44, v37
	v_cvt_pk_bf16_f32 v34, v34, v35
	v_lshlrev_b32_e32 v46, 16, v53
	v_and_b32_e32 v47, 0xffff0000, v53
	s_waitcnt lgkmcnt(0)
	v_mfma_f32_32x32x16_bf16 v[2:17], v[54:57], v[38:41], v[2:17]
	v_cvt_pk_bf16_f32 v38, v36, v37
	v_lshlrev_b32_e32 v36, 16, v51
	v_and_b32_e32 v37, 0xffff0000, v51
	v_mul_f32_e64 v40, v42, v36
	v_mul_f32_e64 v41, v42, v37
	v_cvt_pk_bf16_f32 v35, v40, v41
	v_pk_mul_f32 v[36:37], v[44:45], v[36:37] op_sel_hi:[0,1]
	v_lshlrev_b32_e32 v40, 16, v52
	v_and_b32_e32 v41, 0xffff0000, v52
	v_cvt_pk_bf16_f32 v39, v36, v37
	v_pk_mul_f32 v[36:37], v[42:43], v[40:41] op_sel_hi:[0,1]
	v_pk_mul_f32 v[42:43], v[42:43], v[46:47] op_sel_hi:[0,1]
	v_cvt_pk_bf16_f32 v36, v36, v37
	v_pk_mul_f32 v[40:41], v[44:45], v[40:41] op_sel_hi:[0,1]
	v_cvt_pk_bf16_f32 v37, v42, v43
	v_pk_mul_f32 v[42:43], v[44:45], v[46:47] op_sel_hi:[0,1]
	v_cvt_pk_bf16_f32 v40, v40, v41
	v_cvt_pk_bf16_f32 v41, v42, v43
	ds_read_b128 v[42:45], v99 offset:35936
	ds_read_b128 v[46:49], v99 offset:45152
	s_waitcnt lgkmcnt(1)
	v_mfma_f32_32x32x16_bf16 v[18:33], v[42:45], v[34:37], v[18:33]
	s_waitcnt lgkmcnt(0)
	v_mfma_f32_32x32x16_bf16 v[18:33], v[46:49], v[38:41], v[18:33]
	ds_read_b128 v[42:45], v99 offset:40544
	ds_read_b128 v[46:49], v99 offset:49760
	s_waitcnt lgkmcnt(1)
	v_mfma_f32_32x32x16_bf16 v[2:17], v[42:45], v[34:37], v[2:17]
	s_nop 7
	v_add_f32_e32 v34, 0, v18
	v_add_f32_e32 v34, v19, v34
	v_add_f32_e32 v34, v20, v34
	v_add_f32_e32 v34, v21, v34
	v_add_f32_e32 v34, v22, v34
	v_add_f32_e32 v34, v23, v34
	v_add_f32_e32 v34, v24, v34
	v_add_f32_e32 v34, v25, v34
	s_waitcnt lgkmcnt(0)
	v_mfma_f32_32x32x16_bf16 v[2:17], v[46:49], v[38:41], v[2:17]
	v_add_f32_e32 v34, v26, v34
	v_add_f32_e32 v34, v27, v34
	v_add_f32_e32 v34, v28, v34
	v_add_f32_e32 v34, v29, v34
	v_add_f32_e32 v34, v30, v34
	v_add_f32_e32 v34, v31, v34
	v_add_f32_e32 v34, v32, v34
	v_add_f32_e32 v34, v33, v34
	s_nop 3
	v_add_f32_e32 v34, v2, v34
	v_add_f32_e32 v34, v3, v34
	v_add_f32_e32 v34, v4, v34
	v_add_f32_e32 v34, v5, v34
	v_add_f32_e32 v34, v6, v34
	v_add_f32_e32 v34, v7, v34
	v_add_f32_e32 v34, v8, v34
	v_add_f32_e32 v34, v9, v34
	v_add_f32_e32 v34, v10, v34
	v_add_f32_e32 v34, v11, v34
	v_add_f32_e32 v34, v12, v34
	v_add_f32_e32 v34, v13, v34
	v_add_f32_e32 v34, v14, v34
	v_add_f32_e32 v34, v15, v34
	v_add_f32_e32 v34, v16, v34
	v_add_f32_e32 v34, v17, v34
	ds_bpermute_b32 v35, v97, v34
	v_lshlrev_b64 v[36:37], 11, v[92:93]
	v_lshl_add_u64 v[36:37], s[20:21], 0, v[36:37]
	v_lshlrev_b32_e32 v48, 1, v78
	v_mov_b32_e32 v49, v1
	s_waitcnt lgkmcnt(0)
	v_add_f32_e32 v34, v34, v35
	v_mul_f32_e32 v44, 0x3c800000, v34
	v_pk_add_f32 v[34:35], v[12:13], v[44:45] op_sel_hi:[1,0] neg_lo:[0,1] neg_hi:[0,1]
	v_pk_add_f32 v[12:13], v[16:17], v[44:45] op_sel_hi:[1,0] neg_lo:[0,1] neg_hi:[0,1]
	v_lshl_add_u64 v[16:17], v[94:95], 0, s[0:1]
	v_lshl_add_u64 v[46:47], v[36:37], 0, s[0:1]
	v_lshl_add_u64 v[36:37], v[16:17], 0, v[48:49]
	s_movk_i32 s0, 0x1000
	v_lshl_add_u64 v[16:17], v[36:37], 0, s[4:5]
	v_add_co_u32_e32 v36, vcc, s0, v36
	s_lshl_b32 s0, s6, 2
	s_nop 0
	v_addc_co_u32_e32 v37, vcc, 0, v37, vcc
	global_load_dwordx2 v[50:51], v[36:37], off offset:512
	v_lshl_add_u64 v[36:37], v[86:87], 0, s[0:1]
	v_pk_add_f32 v[14:15], v[14:15], v[44:45] op_sel_hi:[1,0] neg_lo:[0,1] neg_hi:[0,1]
	v_pk_add_f32 v[20:21], v[20:21], v[44:45] op_sel_hi:[1,0] neg_lo:[0,1] neg_hi:[0,1]
	v_pk_add_f32 v[18:19], v[18:19], v[44:45] op_sel_hi:[1,0] neg_lo:[0,1] neg_hi:[0,1]
	v_pk_mul_f32 v[58:59], v[20:21], v[20:21]
	v_pk_mul_f32 v[60:61], v[18:19], v[18:19]
	v_pk_mul_f32 v[38:39], v[34:35], v[34:35]
	v_pk_mul_f32 v[40:41], v[14:15], v[14:15]
	v_pk_mul_f32 v[42:43], v[12:13], v[12:13]
	s_mov_b32 s0, 0x800000
	s_cmpk_gt_i32 s37, 0x17f
	s_waitcnt vmcnt(0)
	v_lshlrev_b32_e32 v54, 16, v50
	v_and_b32_e32 v55, 0xffff0000, v50
	v_lshlrev_b32_e32 v56, 16, v51
	v_and_b32_e32 v57, 0xffff0000, v51
	global_load_dwordx4 v[50:53], v[36:37], off
	global_load_dwordx2 v[140:141], v[16:17], off offset:16
	global_load_dwordx4 v[154:157], v[36:37], off offset:32
	global_load_dwordx2 v[142:143], v[16:17], off offset:32
	global_load_dwordx4 v[158:161], v[36:37], off offset:64
	global_load_dwordx2 v[144:145], v[16:17], off offset:48
	global_load_dwordx4 v[162:165], v[36:37], off offset:96
	global_load_dwordx2 v[146:147], v[16:17], off offset:64
	global_load_dwordx4 v[166:169], v[36:37], off offset:128
	global_load_dwordx2 v[148:149], v[16:17], off offset:80
	global_load_dwordx4 v[170:173], v[36:37], off offset:160
	global_load_dwordx2 v[150:151], v[16:17], off offset:96
	global_load_dwordx4 v[174:177], v[36:37], off offset:192
	global_load_dwordx2 v[152:153], v[16:17], off offset:112
	global_load_dwordx4 v[178:181], v[36:37], off offset:224
	v_mul_f32_e32 v45, 0xbfb8aa3b, v54
	v_exp_f32_e32 v45, v45
	s_nop 0
	v_add_f32_e32 v45, 1.0, v45
	v_rcp_f32_e32 v62, v45
	v_mul_f32_e32 v45, 0xbfb8aa3b, v55
	v_exp_f32_e32 v45, v45
	s_nop 0
	v_add_f32_e32 v45, 1.0, v45
	v_rcp_f32_e32 v63, v45
	v_pk_add_f32 v[28:29], v[28:29], v[44:45] op_sel_hi:[1,0] neg_lo:[0,1] neg_hi:[0,1]
	v_pk_add_f32 v[94:95], v[26:27], v[44:45] op_sel_hi:[1,0] neg_lo:[0,1] neg_hi:[0,1]
	v_pk_add_f32 v[26:27], v[30:31], v[44:45] op_sel_hi:[1,0] neg_lo:[0,1] neg_hi:[0,1]
	v_pk_mul_f32 v[54:55], v[62:63], v[54:55]
	v_pk_add_f32 v[62:63], v[22:23], v[44:45] op_sel_hi:[1,0] neg_lo:[0,1] neg_hi:[0,1]
	v_pk_mul_f32 v[54:55], v[54:55], v[18:19]
	v_mul_f32_e32 v18, 0xbfb8aa3b, v56
	v_mul_f32_e32 v19, 0xbfb8aa3b, v57
	v_exp_f32_e32 v18, v18
	v_exp_f32_e32 v19, v19
	v_pk_add_f32 v[22:23], v[2:3], v[44:45] op_sel_hi:[1,0] neg_lo:[0,1] neg_hi:[0,1]
	v_pk_add_f32 v[8:9], v[8:9], v[44:45] op_sel_hi:[1,0] neg_lo:[0,1] neg_hi:[0,1]
	v_add_f32_e32 v18, 1.0, v18
	v_add_f32_e32 v19, 1.0, v19
	v_rcp_f32_e32 v18, v18
	v_rcp_f32_e32 v19, v19
	v_pk_add_f32 v[6:7], v[6:7], v[44:45] op_sel_hi:[1,0] neg_lo:[0,1] neg_hi:[0,1]
	v_pk_mul_f32 v[64:65], v[62:63], v[62:63]
	v_pk_mul_f32 v[106:107], v[94:95], v[94:95]
	v_pk_mul_f32 v[18:19], v[18:19], v[56:57]
	v_pk_mul_f32 v[92:93], v[28:29], v[28:29]
	v_pk_mul_f32 v[56:57], v[18:19], v[20:21]
	v_lshl_add_u64 v[18:19], v[46:47], 0, v[48:49]
	v_pk_add_f32 v[46:47], v[24:25], v[44:45] op_sel_hi:[1,0] neg_lo:[0,1] neg_hi:[0,1]
	v_pk_add_f32 v[24:25], v[32:33], v[44:45] op_sel_hi:[1,0] neg_lo:[0,1] neg_hi:[0,1]
	v_pk_add_f32 v[20:21], v[4:5], v[44:45] op_sel_hi:[1,0] neg_lo:[0,1] neg_hi:[0,1]
	v_pk_add_f32 v[4:5], v[10:11], v[44:45] op_sel_hi:[1,0] neg_lo:[0,1] neg_hi:[0,1]
	v_add_f32_e32 v44, v60, v61
	v_add_f32_e32 v44, v58, v44
	v_add_f32_e32 v44, v59, v44
	v_add_f32_e32 v44, v64, v44
	v_pk_mul_f32 v[48:49], v[46:47], v[46:47]
	v_add_f32_e32 v44, v65, v44
	v_add_f32_e32 v44, v48, v44
	v_add_f32_e32 v44, v49, v44
	v_add_f32_e32 v44, v106, v44
	v_add_f32_e32 v44, v107, v44
	v_add_f32_e32 v44, v92, v44
	v_pk_mul_f32 v[30:31], v[26:27], v[26:27]
	v_add_f32_e32 v44, v93, v44
	v_add_f32_e32 v30, v30, v44
	v_pk_mul_f32 v[32:33], v[24:25], v[24:25]
	v_add_f32_e32 v30, v31, v30
	v_add_f32_e32 v30, v32, v30
	v_pk_mul_f32 v[2:3], v[22:23], v[22:23]
	v_add_f32_e32 v30, v33, v30
	v_add_f32_e32 v2, v2, v30
	v_pk_mul_f32 v[108:109], v[20:21], v[20:21]
	v_add_f32_e32 v2, v3, v2
	v_add_f32_e32 v2, v108, v2
	v_pk_mul_f32 v[112:113], v[6:7], v[6:7]
	v_add_f32_e32 v2, v109, v2
	v_add_f32_e32 v2, v112, v2
	v_pk_mul_f32 v[110:111], v[8:9], v[8:9]
	v_add_f32_e32 v2, v113, v2
	v_add_f32_e32 v2, v110, v2
	v_pk_mul_f32 v[10:11], v[4:5], v[4:5]
	v_add_f32_e32 v2, v111, v2
	v_add_f32_e32 v2, v10, v2
	v_add_f32_e32 v2, v11, v2
	v_add_f32_e32 v2, v38, v2
	v_add_f32_e32 v2, v39, v2
	v_add_f32_e32 v2, v40, v2
	v_add_f32_e32 v2, v41, v2
	v_add_f32_e32 v2, v42, v2
	v_add_f32_e32 v2, v43, v2
	ds_bpermute_b32 v3, v97, v2
	s_waitcnt lgkmcnt(0)
	v_add_f32_e32 v2, v2, v3
	v_fmamk_f32 v2, v2, 0x3c800000, v210
	v_cmp_gt_f32_e32 vcc, s0, v2
	v_mul_f32_e32 v3, 0x4b800000, v2
	s_nop 0
	v_cndmask_b32_e32 v2, v2, v3, vcc
	v_rsq_f32_e32 v2, v2
	s_nop 0
	v_mul_f32_e32 v3, 0x45800000, v2
	v_cndmask_b32_e32 v2, v2, v3, vcc
	v_pk_mul_f32 v[10:11], v[54:55], v[2:3] op_sel_hi:[1,0]
	v_pk_mul_f32 v[30:31], v[56:57], v[2:3] op_sel_hi:[1,0]
	s_waitcnt vmcnt(14)
	v_pk_mul_f32 v[10:11], v[50:51], v[10:11]
	v_pk_mul_f32 v[30:31], v[52:53], v[30:31]
	v_cvt_pk_bf16_f32 v10, v10, v11
	v_cvt_pk_bf16_f32 v11, v30, v31
	global_store_dwordx2 v[18:19], v[10:11], off offset:1536
	s_nop 0
	s_waitcnt vmcnt(14)
	v_lshlrev_b32_e32 v38, 16, v140
	v_mul_f32_e32 v3, 0xbfb8aa3b, v38
	v_exp_f32_e32 v3, v3
	v_and_b32_e32 v39, 0xffff0000, v140
	v_lshlrev_b32_e32 v10, 16, v141
	v_and_b32_e32 v11, 0xffff0000, v141
	v_add_f32_e32 v3, 1.0, v3
	v_rcp_f32_e32 v40, v3
	v_mul_f32_e32 v3, 0xbfb8aa3b, v39
	v_exp_f32_e32 v3, v3
	s_nop 0
	v_add_f32_e32 v3, 1.0, v3
	v_rcp_f32_e32 v41, v3
	s_nop 0
	v_pk_mul_f32 v[38:39], v[40:41], v[38:39]
	s_nop 0
	v_pk_mul_f32 v[38:39], v[38:39], v[62:63]
	s_nop 0
	v_pk_mul_f32 v[38:39], v[38:39], v[2:3] op_sel_hi:[1,0]
	v_mul_f32_e32 v3, 0xbfb8aa3b, v10
	v_exp_f32_e32 v3, v3
	s_waitcnt vmcnt(13)
	v_pk_mul_f32 v[30:31], v[154:155], v[38:39]
	v_add_f32_e32 v3, 1.0, v3
	v_rcp_f32_e32 v38, v3
	v_mul_f32_e32 v3, 0xbfb8aa3b, v11
	v_exp_f32_e32 v3, v3
	v_cvt_pk_bf16_f32 v30, v30, v31
	v_add_f32_e32 v3, 1.0, v3
	v_rcp_f32_e32 v39, v3
	s_nop 0
	v_pk_mul_f32 v[10:11], v[38:39], v[10:11]
	s_nop 0
	v_pk_mul_f32 v[10:11], v[10:11], v[46:47]
	s_nop 0
	v_pk_mul_f32 v[10:11], v[10:11], v[2:3] op_sel_hi:[1,0]
	s_nop 0
	v_pk_mul_f32 v[10:11], v[156:157], v[10:11]
	s_nop 0
	v_cvt_pk_bf16_f32 v31, v10, v11
	global_store_dwordx2 v[18:19], v[30:31], off offset:1552
	s_nop 0
	s_waitcnt vmcnt(13)
	v_lshlrev_b32_e32 v38, 16, v142
	v_mul_f32_e32 v3, 0xbfb8aa3b, v38
	v_exp_f32_e32 v3, v3
	v_and_b32_e32 v39, 0xffff0000, v142
	v_lshlrev_b32_e32 v10, 16, v143
	v_and_b32_e32 v11, 0xffff0000, v143
	v_add_f32_e32 v3, 1.0, v3
	v_rcp_f32_e32 v40, v3
	v_mul_f32_e32 v3, 0xbfb8aa3b, v39
	v_exp_f32_e32 v3, v3
	s_nop 0
	v_add_f32_e32 v3, 1.0, v3
	v_rcp_f32_e32 v41, v3
	s_nop 0
	v_pk_mul_f32 v[38:39], v[40:41], v[38:39]
	s_nop 0
	v_pk_mul_f32 v[38:39], v[38:39], v[94:95]
	s_nop 0
	v_pk_mul_f32 v[38:39], v[38:39], v[2:3] op_sel_hi:[1,0]
	v_mul_f32_e32 v3, 0xbfb8aa3b, v10
	v_exp_f32_e32 v3, v3
	s_waitcnt vmcnt(12)
	v_pk_mul_f32 v[30:31], v[158:159], v[38:39]
	v_add_f32_e32 v3, 1.0, v3
	v_rcp_f32_e32 v38, v3
	v_mul_f32_e32 v3, 0xbfb8aa3b, v11
	v_exp_f32_e32 v3, v3
	s_nop 0
	v_add_f32_e32 v3, 1.0, v3
	v_rcp_f32_e32 v39, v3
	s_nop 0
	v_pk_mul_f32 v[10:11], v[38:39], v[10:11]
	s_nop 0
	v_pk_mul_f32 v[10:11], v[10:11], v[28:29]
	v_cvt_pk_bf16_f32 v28, v30, v31
	v_pk_mul_f32 v[10:11], v[10:11], v[2:3] op_sel_hi:[1,0]
	s_nop 0
	v_pk_mul_f32 v[10:11], v[160:161], v[10:11]
	s_nop 0
	v_cvt_pk_bf16_f32 v29, v10, v11
	global_store_dwordx2 v[18:19], v[28:29], off offset:1568
	s_nop 0
	s_waitcnt vmcnt(12)
	v_lshlrev_b32_e32 v32, 16, v144
	v_mul_f32_e32 v3, 0xbfb8aa3b, v32
	v_exp_f32_e32 v3, v3
	v_and_b32_e32 v33, 0xffff0000, v144
	v_lshlrev_b32_e32 v10, 16, v145
	v_and_b32_e32 v11, 0xffff0000, v145
	v_add_f32_e32 v3, 1.0, v3
	v_rcp_f32_e32 v38, v3
	v_mul_f32_e32 v3, 0xbfb8aa3b, v33
	v_exp_f32_e32 v3, v3
	s_nop 0
	v_add_f32_e32 v3, 1.0, v3
	v_rcp_f32_e32 v39, v3
	s_nop 0
	v_pk_mul_f32 v[32:33], v[38:39], v[32:33]
	s_nop 0
	v_pk_mul_f32 v[26:27], v[32:33], v[26:27]
	s_nop 0
	v_pk_mul_f32 v[26:27], v[26:27], v[2:3] op_sel_hi:[1,0]
	v_mul_f32_e32 v3, 0xbfb8aa3b, v10
	v_exp_f32_e32 v3, v3
	s_waitcnt vmcnt(11)
	v_pk_mul_f32 v[26:27], v[162:163], v[26:27]
	v_add_f32_e32 v3, 1.0, v3
	v_rcp_f32_e32 v28, v3
	v_mul_f32_e32 v3, 0xbfb8aa3b, v11
	v_exp_f32_e32 v3, v3
	s_nop 0
	v_add_f32_e32 v3, 1.0, v3
	v_rcp_f32_e32 v29, v3
	s_nop 0
	v_pk_mul_f32 v[10:11], v[28:29], v[10:11]
	s_nop 0
	v_pk_mul_f32 v[10:11], v[10:11], v[24:25]
	v_cvt_pk_bf16_f32 v24, v26, v27
	v_pk_mul_f32 v[10:11], v[10:11], v[2:3] op_sel_hi:[1,0]
	s_nop 0
	v_pk_mul_f32 v[10:11], v[164:165], v[10:11]
	s_nop 0
	v_cvt_pk_bf16_f32 v25, v10, v11
	global_store_dwordx2 v[18:19], v[24:25], off offset:1584
	s_nop 0
	s_waitcnt vmcnt(11)
	v_lshlrev_b32_e32 v28, 16, v146
	v_mul_f32_e32 v3, 0xbfb8aa3b, v28
	v_exp_f32_e32 v3, v3
	v_and_b32_e32 v29, 0xffff0000, v146
	v_lshlrev_b32_e32 v10, 16, v147
	v_and_b32_e32 v11, 0xffff0000, v147
	v_add_f32_e32 v3, 1.0, v3
	v_rcp_f32_e32 v30, v3
	v_mul_f32_e32 v3, 0xbfb8aa3b, v29
	v_exp_f32_e32 v3, v3
	s_nop 0
	v_add_f32_e32 v3, 1.0, v3
	v_rcp_f32_e32 v31, v3
	s_nop 0
	v_pk_mul_f32 v[28:29], v[30:31], v[28:29]
	s_nop 0
	v_pk_mul_f32 v[22:23], v[22:23], v[28:29]
	s_nop 0
	v_pk_mul_f32 v[22:23], v[22:23], v[2:3] op_sel_hi:[1,0]
	v_mul_f32_e32 v3, 0xbfb8aa3b, v10
	v_exp_f32_e32 v3, v3
	s_waitcnt vmcnt(10)
	v_pk_mul_f32 v[22:23], v[166:167], v[22:23]
	v_add_f32_e32 v3, 1.0, v3
	v_rcp_f32_e32 v24, v3
	v_mul_f32_e32 v3, 0xbfb8aa3b, v11
	v_exp_f32_e32 v3, v3
	s_nop 0
	v_add_f32_e32 v3, 1.0, v3
	v_rcp_f32_e32 v25, v3
	s_nop 0
	v_pk_mul_f32 v[10:11], v[24:25], v[10:11]
	s_nop 0
	v_pk_mul_f32 v[10:11], v[20:21], v[10:11]
	v_cvt_pk_bf16_f32 v20, v22, v23
	v_pk_mul_f32 v[10:11], v[10:11], v[2:3] op_sel_hi:[1,0]
	s_nop 0
	v_pk_mul_f32 v[10:11], v[168:169], v[10:11]
	s_nop 0
	v_cvt_pk_bf16_f32 v21, v10, v11
	global_store_dwordx2 v[18:19], v[20:21], off offset:1600
	s_nop 0
	s_waitcnt vmcnt(10)
	v_lshlrev_b32_e32 v24, 16, v148
	v_mul_f32_e32 v3, 0xbfb8aa3b, v24
	v_exp_f32_e32 v3, v3
	v_and_b32_e32 v25, 0xffff0000, v148
	v_lshlrev_b32_e32 v10, 16, v149
	v_and_b32_e32 v11, 0xffff0000, v149
	v_add_f32_e32 v3, 1.0, v3
	v_rcp_f32_e32 v26, v3
	v_mul_f32_e32 v3, 0xbfb8aa3b, v25
	v_exp_f32_e32 v3, v3
	s_nop 0
	v_add_f32_e32 v3, 1.0, v3
	v_rcp_f32_e32 v27, v3
	s_nop 0
	v_pk_mul_f32 v[24:25], v[26:27], v[24:25]
	s_nop 0
	v_pk_mul_f32 v[6:7], v[6:7], v[24:25]
	s_nop 0
	v_pk_mul_f32 v[6:7], v[6:7], v[2:3] op_sel_hi:[1,0]
	v_mul_f32_e32 v3, 0xbfb8aa3b, v10
	v_exp_f32_e32 v3, v3
	s_waitcnt vmcnt(9)
	v_pk_mul_f32 v[6:7], v[170:171], v[6:7]
	v_add_f32_e32 v3, 1.0, v3
	v_rcp_f32_e32 v20, v3
	v_mul_f32_e32 v3, 0xbfb8aa3b, v11
	v_exp_f32_e32 v3, v3
	v_cvt_pk_bf16_f32 v6, v6, v7
	v_add_f32_e32 v3, 1.0, v3
	v_rcp_f32_e32 v21, v3
	s_nop 0
	v_pk_mul_f32 v[10:11], v[20:21], v[10:11]
	s_nop 0
	v_pk_mul_f32 v[8:9], v[8:9], v[10:11]
	s_nop 0
	v_pk_mul_f32 v[8:9], v[8:9], v[2:3] op_sel_hi:[1,0]
	s_nop 0
	v_pk_mul_f32 v[8:9], v[172:173], v[8:9]
	s_nop 0
	v_cvt_pk_bf16_f32 v7, v8, v9
	global_store_dwordx2 v[18:19], v[6:7], off offset:1616
	s_nop 0
	s_waitcnt vmcnt(9)
	v_lshlrev_b32_e32 v20, 16, v150
	v_mul_f32_e32 v3, 0xbfb8aa3b, v20
	v_exp_f32_e32 v3, v3
	v_and_b32_e32 v21, 0xffff0000, v150
	v_add_f32_e32 v3, 1.0, v3
	v_rcp_f32_e32 v22, v3
	v_mul_f32_e32 v3, 0xbfb8aa3b, v21
	v_exp_f32_e32 v3, v3
	s_nop 0
	v_add_f32_e32 v3, 1.0, v3
	v_rcp_f32_e32 v23, v3
	s_nop 0
	v_pk_mul_f32 v[20:21], v[22:23], v[20:21]
	s_nop 0
	v_pk_mul_f32 v[4:5], v[4:5], v[20:21]
	s_nop 0
	v_pk_mul_f32 v[4:5], v[4:5], v[2:3] op_sel_hi:[1,0]
	s_waitcnt vmcnt(8)
	v_pk_mul_f32 v[4:5], v[174:175], v[4:5]
	v_lshlrev_b32_e32 v6, 16, v151
	v_mul_f32_e32 v3, 0xbfb8aa3b, v6
	v_exp_f32_e32 v3, v3
	v_and_b32_e32 v7, 0xffff0000, v151
	v_cvt_pk_bf16_f32 v4, v4, v5
	v_add_f32_e32 v3, 1.0, v3
	v_rcp_f32_e32 v10, v3
	v_mul_f32_e32 v3, 0xbfb8aa3b, v7
	v_exp_f32_e32 v3, v3
	s_nop 0
	v_add_f32_e32 v3, 1.0, v3
	v_rcp_f32_e32 v11, v3
	s_nop 0
	v_pk_mul_f32 v[6:7], v[10:11], v[6:7]
	s_nop 0
	v_pk_mul_f32 v[6:7], v[34:35], v[6:7]
	s_nop 0
	v_pk_mul_f32 v[6:7], v[6:7], v[2:3] op_sel_hi:[1,0]
	s_nop 0
	v_pk_mul_f32 v[6:7], v[176:177], v[6:7]
	s_nop 0
	v_cvt_pk_bf16_f32 v5, v6, v7
	global_store_dwordx2 v[18:19], v[4:5], off offset:1632
	s_waitcnt vmcnt(8)
	v_lshlrev_b32_e32 v10, 16, v152
	v_mul_f32_e32 v3, 0xbfb8aa3b, v10
	v_exp_f32_e32 v3, v3
	v_and_b32_e32 v11, 0xffff0000, v152
	v_lshlrev_b32_e32 v8, 16, v153
	v_and_b32_e32 v9, 0xffff0000, v153
	v_add_f32_e32 v3, 1.0, v3
	v_rcp_f32_e32 v16, v3
	v_mul_f32_e32 v3, 0xbfb8aa3b, v11
	v_exp_f32_e32 v3, v3
	s_nop 0
	v_add_f32_e32 v3, 1.0, v3
	v_rcp_f32_e32 v17, v3
	s_nop 0
	v_pk_mul_f32 v[10:11], v[16:17], v[10:11]
	s_nop 0
	v_pk_mul_f32 v[10:11], v[14:15], v[10:11]
	s_nop 0
	v_pk_mul_f32 v[10:11], v[10:11], v[2:3] op_sel_hi:[1,0]
	v_mul_f32_e32 v3, 0xbfb8aa3b, v8
	v_exp_f32_e32 v3, v3
	s_waitcnt vmcnt(7)
	v_pk_mul_f32 v[4:5], v[178:179], v[10:11]
	v_add_f32_e32 v3, 1.0, v3
	v_rcp_f32_e32 v10, v3
	v_mul_f32_e32 v3, 0xbfb8aa3b, v9
	v_exp_f32_e32 v3, v3
	v_cvt_pk_bf16_f32 v4, v4, v5
	v_add_f32_e32 v3, 1.0, v3
	v_rcp_f32_e32 v11, v3
	s_nop 0
	v_pk_mul_f32 v[8:9], v[10:11], v[8:9]
	s_nop 0
	v_pk_mul_f32 v[8:9], v[12:13], v[8:9]
	s_nop 0
	v_pk_mul_f32 v[2:3], v[8:9], v[2:3] op_sel_hi:[1,0]
	s_nop 0
	v_pk_mul_f32 v[2:3], v[180:181], v[2:3]
	s_nop 0
	v_cvt_pk_bf16_f32 v5, v2, v3
	global_store_dwordx2 v[18:19], v[4:5], off offset:1648
	s_cbranch_scc1 .LBB0_1053
